# v13 plus: first K-loop iteration of three GEMM variants peeled with zero accumulator input, removing the 128 v_mov zero-init per tile
# speedup vs baseline: 1.0031x; 1.0031x over previous
.LBB0_307:
	s_add_u32 vcc_lo, s82, 0x80
	s_addc_u32 vcc_hi, s83, 0
	s_add_u32 s82, s42, 0x100
	s_addc_u32 s83, s43, 0
	s_mov_b32 s42, 0
	s_add_i32 s72, s42, 2
	s_add_u32 s73, vcc_lo, 0x80
	s_addc_u32 s43, vcc_hi, 0
	s_add_i32 s45, 0, 0x10000
	s_cmp_eq_u32 s63, s42
	s_cselect_b32 s43, s9, s43
	s_cselect_b32 s42, s8, s73
	v_add_u32_e32 v140, s45, v143
	s_cselect_b32 s75, s91, s83
	s_cselect_b32 s74, s90, s82
	s_add_i32 s73, 0, 0x14000
	ds_read_b128 v[146:149], v140
	ds_read_b128 v[150:153], v140 offset:1024
	ds_read_b128 v[154:157], v140 offset:2048
	ds_read_b128 v[158:161], v140 offset:3072
	v_add_u32_e32 v140, s73, v143
	ds_read_b128 v[162:165], v140
	ds_read_b128 v[166:169], v140 offset:1024
	ds_read_b128 v[170:173], v140 offset:2048
	ds_read_b128 v[174:177], v140 offset:3072
	v_lshl_add_u64 v[140:141], vcc, 0, v[136:137]
	s_add_i32 m0, s59, 0xc000
	ds_read_b128 v[178:181], v145
	ds_read_b128 v[182:185], v145 offset:1024
	ds_read_b128 v[186:189], v145 offset:2048
	ds_read_b128 v[190:193], v145 offset:3072
	ds_read_b128 v[202:205], v145 offset:4096
	ds_read_b128 v[206:209], v145 offset:5120
	ds_read_b128 v[220:223], v145 offset:6144
	ds_read_b128 v[224:227], v145 offset:7168
	global_load_lds_dwordx4 v[140:141], off
	v_lshl_add_u64 v[140:141], vcc, 0, v[138:139]
	s_add_i32 m0, s59, 0xe000
	s_nop 0
	global_load_lds_dwordx4 v[140:141], off
	s_waitcnt vmcnt(8)
	s_waitcnt lgkmcnt(0)
	s_barrier
	s_setprio 1
	s_waitcnt lgkmcnt(0)
	v_mfma_f32_16x16x32_bf16 v[126:129], v[146:149], v[178:181], 0
	v_mfma_f32_16x16x32_bf16 v[122:125], v[154:157], v[178:181], 0
	v_mfma_f32_16x16x32_bf16 v[118:121], v[146:149], v[186:189], 0
	v_mfma_f32_16x16x32_bf16 v[110:113], v[154:157], v[186:189], 0
	v_mfma_f32_16x16x32_bf16 v[102:105], v[146:149], v[202:205], 0
	v_mfma_f32_16x16x32_bf16 v[94:97], v[154:157], v[202:205], 0
	v_mfma_f32_16x16x32_bf16 v[86:89], v[146:149], v[220:223], 0
	v_mfma_f32_16x16x32_bf16 v[78:81], v[154:157], v[220:223], 0
	v_mfma_f32_16x16x32_bf16 v[126:129], v[150:153], v[182:185], v[126:129]
	v_mfma_f32_16x16x32_bf16 v[122:125], v[158:161], v[182:185], v[122:125]
	v_mfma_f32_16x16x32_bf16 v[118:121], v[150:153], v[190:193], v[118:121]
	v_mfma_f32_16x16x32_bf16 v[110:113], v[158:161], v[190:193], v[110:113]
	v_mfma_f32_16x16x32_bf16 v[102:105], v[150:153], v[206:209], v[102:105]
	v_mfma_f32_16x16x32_bf16 v[94:97], v[158:161], v[206:209], v[94:97]
	v_mfma_f32_16x16x32_bf16 v[86:89], v[150:153], v[224:227], v[86:89]
	v_mfma_f32_16x16x32_bf16 v[78:81], v[158:161], v[224:227], v[78:81]
	s_setprio 0
	s_setprio 1
	v_mfma_f32_16x16x32_bf16 v[114:117], v[162:165], v[178:181], 0
	v_mfma_f32_16x16x32_bf16 v[106:109], v[170:173], v[178:181], 0
	v_mfma_f32_16x16x32_bf16 v[98:101], v[162:165], v[186:189], 0
	v_mfma_f32_16x16x32_bf16 v[90:93], v[170:173], v[186:189], 0
	v_mfma_f32_16x16x32_bf16 v[82:85], v[162:165], v[202:205], 0
	v_mfma_f32_16x16x32_bf16 v[74:77], v[170:173], v[202:205], 0
	v_mfma_f32_16x16x32_bf16 v[70:73], v[162:165], v[220:223], 0
	v_mfma_f32_16x16x32_bf16 v[66:69], v[170:173], v[220:223], 0
	v_mfma_f32_16x16x32_bf16 v[114:117], v[166:169], v[182:185], v[114:117]
	v_mfma_f32_16x16x32_bf16 v[106:109], v[174:177], v[182:185], v[106:109]
	v_mfma_f32_16x16x32_bf16 v[98:101], v[166:169], v[190:193], v[98:101]
	v_mfma_f32_16x16x32_bf16 v[90:93], v[174:177], v[190:193], v[90:93]
	v_mfma_f32_16x16x32_bf16 v[82:85], v[166:169], v[206:209], v[82:85]
	v_mfma_f32_16x16x32_bf16 v[74:77], v[174:177], v[206:209], v[74:77]
	v_mfma_f32_16x16x32_bf16 v[70:73], v[166:169], v[224:227], v[70:73]
	v_mfma_f32_16x16x32_bf16 v[66:69], v[174:177], v[224:227], v[66:69]
	s_setprio 0
	s_barrier
	s_add_i32 s45, s45, s54
	v_lshl_add_u64 v[140:141], s[74:75], 0, v[0:1]
	s_mov_b32 m0, s45
	ds_read_b128 v[178:181], v145 offset:16384
	ds_read_b128 v[182:185], v145 offset:17408
	ds_read_b128 v[186:189], v145 offset:18432
	ds_read_b128 v[190:193], v145 offset:19456
	ds_read_b128 v[202:205], v145 offset:20480
	ds_read_b128 v[206:209], v145 offset:21504
	ds_read_b128 v[220:223], v145 offset:22528
	ds_read_b128 v[224:227], v145 offset:23552
	global_load_lds_dwordx4 v[140:141], off
	s_add_i32 m0, s45, 0x2000
	v_lshl_add_u64 v[194:195], s[74:75], 0, v[134:135]
	s_add_u32 s74, s74, s80
	s_addc_u32 s75, s75, 0
	s_add_i32 s45, s73, s54
	global_load_lds_dwordx4 v[194:195], off
	v_lshl_add_u64 v[198:199], s[74:75], 0, v[0:1]
	s_mov_b32 m0, s45
	v_lshl_add_u64 v[200:201], s[74:75], 0, v[134:135]
	global_load_lds_dwordx4 v[198:199], off
	s_add_i32 m0, s45, 0x2000
	v_lshl_add_u64 v[210:211], s[42:43], 0, v[130:131]
	global_load_lds_dwordx4 v[200:201], off
	s_mov_b32 m0, s59
	v_lshl_add_u64 v[212:213], s[42:43], 0, v[132:133]
	global_load_lds_dwordx4 v[210:211], off
	s_mov_b32 m0, s60
	s_nop 0
	global_load_lds_dwordx4 v[212:213], off
	s_waitcnt vmcnt(8)
	s_waitcnt lgkmcnt(0)
	s_barrier
	s_setprio 1
	s_waitcnt lgkmcnt(0)
	v_mfma_f32_16x16x32_bf16 v[62:65], v[146:149], v[178:181], 0
	v_mfma_f32_16x16x32_bf16 v[58:61], v[154:157], v[178:181], 0
	v_mfma_f32_16x16x32_bf16 v[54:57], v[146:149], v[186:189], 0
	v_mfma_f32_16x16x32_bf16 v[46:49], v[154:157], v[186:189], 0
	v_mfma_f32_16x16x32_bf16 v[38:41], v[146:149], v[202:205], 0
	v_mfma_f32_16x16x32_bf16 v[30:33], v[154:157], v[202:205], 0
	v_mfma_f32_16x16x32_bf16 v[22:25], v[146:149], v[220:223], 0
	v_mfma_f32_16x16x32_bf16 v[14:17], v[154:157], v[220:223], 0
	v_mfma_f32_16x16x32_bf16 v[62:65], v[150:153], v[182:185], v[62:65]
	v_mfma_f32_16x16x32_bf16 v[58:61], v[158:161], v[182:185], v[58:61]
	v_mfma_f32_16x16x32_bf16 v[54:57], v[150:153], v[190:193], v[54:57]
	v_mfma_f32_16x16x32_bf16 v[46:49], v[158:161], v[190:193], v[46:49]
	v_mfma_f32_16x16x32_bf16 v[38:41], v[150:153], v[206:209], v[38:41]
	v_mfma_f32_16x16x32_bf16 v[30:33], v[158:161], v[206:209], v[30:33]
	v_mfma_f32_16x16x32_bf16 v[22:25], v[150:153], v[224:227], v[22:25]
	v_mfma_f32_16x16x32_bf16 v[14:17], v[158:161], v[224:227], v[14:17]
	s_setprio 0
	s_setprio 1
	v_mfma_f32_16x16x32_bf16 v[50:53], v[162:165], v[178:181], 0
	v_mfma_f32_16x16x32_bf16 v[42:45], v[170:173], v[178:181], 0
	v_mfma_f32_16x16x32_bf16 v[34:37], v[162:165], v[186:189], 0
	v_mfma_f32_16x16x32_bf16 v[26:29], v[170:173], v[186:189], 0
	v_mfma_f32_16x16x32_bf16 v[18:21], v[162:165], v[202:205], 0
	v_mfma_f32_16x16x32_bf16 v[10:13], v[170:173], v[202:205], 0
	v_mfma_f32_16x16x32_bf16 v[6:9], v[162:165], v[220:223], 0
	v_mfma_f32_16x16x32_bf16 v[2:5], v[170:173], v[220:223], 0
	v_mfma_f32_16x16x32_bf16 v[50:53], v[166:169], v[182:185], v[50:53]
	v_mfma_f32_16x16x32_bf16 v[42:45], v[174:177], v[182:185], v[42:45]
	v_mfma_f32_16x16x32_bf16 v[34:37], v[166:169], v[190:193], v[34:37]
	v_mfma_f32_16x16x32_bf16 v[26:29], v[174:177], v[190:193], v[26:29]
	v_mfma_f32_16x16x32_bf16 v[18:21], v[166:169], v[206:209], v[18:21]
	v_mfma_f32_16x16x32_bf16 v[10:13], v[174:177], v[206:209], v[10:13]
	v_mfma_f32_16x16x32_bf16 v[6:9], v[166:169], v[224:227], v[6:9]
	v_mfma_f32_16x16x32_bf16 v[2:5], v[174:177], v[224:227], v[2:5]
	s_setprio 0
	s_barrier
	s_add_i32 s45, 0, 0x18000
	s_add_i32 s73, 0, 0x1c000
	v_add_u32_e32 v158, s45, v143
	v_add_u32_e32 v174, s73, v143
	ds_read_b128 v[146:149], v158
	ds_read_b128 v[150:153], v158 offset:1024
	ds_read_b128 v[154:157], v158 offset:2048
	ds_read_b128 v[158:161], v158 offset:3072
	ds_read_b128 v[162:165], v174
	ds_read_b128 v[166:169], v174 offset:1024
	ds_read_b128 v[170:173], v174 offset:2048
	ds_read_b128 v[174:177], v174 offset:3072
	s_add_u32 s42, s42, s80
	s_addc_u32 s43, s43, 0
	s_mov_b32 m0, s61
	v_lshl_add_u64 v[214:215], s[42:43], 0, v[130:131]
	ds_read_b128 v[178:181], v145 offset:32768
	ds_read_b128 v[182:185], v145 offset:33792
	ds_read_b128 v[186:189], v145 offset:34816
	ds_read_b128 v[190:193], v145 offset:35840
	ds_read_b128 v[202:205], v145 offset:36864
	ds_read_b128 v[206:209], v145 offset:37888
	ds_read_b128 v[220:223], v145 offset:38912
	ds_read_b128 v[224:227], v145 offset:39936
	global_load_lds_dwordx4 v[214:215], off
	v_lshl_add_u64 v[214:215], s[42:43], 0, v[132:133]
	s_mov_b32 m0, s62
	s_nop 0
	global_load_lds_dwordx4 v[214:215], off
	s_waitcnt vmcnt(8)
	s_waitcnt lgkmcnt(0)
	s_barrier
	s_setprio 1
	s_waitcnt lgkmcnt(0)
	v_mfma_f32_16x16x32_bf16 v[126:129], v[146:149], v[178:181], v[126:129]
	v_mfma_f32_16x16x32_bf16 v[122:125], v[154:157], v[178:181], v[122:125]
	v_mfma_f32_16x16x32_bf16 v[118:121], v[146:149], v[186:189], v[118:121]
	v_mfma_f32_16x16x32_bf16 v[110:113], v[154:157], v[186:189], v[110:113]
	v_mfma_f32_16x16x32_bf16 v[102:105], v[146:149], v[202:205], v[102:105]
	v_mfma_f32_16x16x32_bf16 v[94:97], v[154:157], v[202:205], v[94:97]
	v_mfma_f32_16x16x32_bf16 v[86:89], v[146:149], v[220:223], v[86:89]
	v_mfma_f32_16x16x32_bf16 v[78:81], v[154:157], v[220:223], v[78:81]
	v_mfma_f32_16x16x32_bf16 v[126:129], v[150:153], v[182:185], v[126:129]
	v_mfma_f32_16x16x32_bf16 v[122:125], v[158:161], v[182:185], v[122:125]
	v_mfma_f32_16x16x32_bf16 v[118:121], v[150:153], v[190:193], v[118:121]
	v_mfma_f32_16x16x32_bf16 v[110:113], v[158:161], v[190:193], v[110:113]
	v_mfma_f32_16x16x32_bf16 v[102:105], v[150:153], v[206:209], v[102:105]
	v_mfma_f32_16x16x32_bf16 v[94:97], v[158:161], v[206:209], v[94:97]
	v_mfma_f32_16x16x32_bf16 v[86:89], v[150:153], v[224:227], v[86:89]
	v_mfma_f32_16x16x32_bf16 v[78:81], v[158:161], v[224:227], v[78:81]
	s_setprio 0
	s_setprio 1
	v_mfma_f32_16x16x32_bf16 v[114:117], v[162:165], v[178:181], v[114:117]
	v_mfma_f32_16x16x32_bf16 v[106:109], v[170:173], v[178:181], v[106:109]
	v_mfma_f32_16x16x32_bf16 v[98:101], v[162:165], v[186:189], v[98:101]
	v_mfma_f32_16x16x32_bf16 v[90:93], v[170:173], v[186:189], v[90:93]
	v_mfma_f32_16x16x32_bf16 v[82:85], v[162:165], v[202:205], v[82:85]
	v_mfma_f32_16x16x32_bf16 v[74:77], v[170:173], v[202:205], v[74:77]
	v_mfma_f32_16x16x32_bf16 v[70:73], v[162:165], v[220:223], v[70:73]
	v_mfma_f32_16x16x32_bf16 v[66:69], v[170:173], v[220:223], v[66:69]
	v_mfma_f32_16x16x32_bf16 v[114:117], v[166:169], v[182:185], v[114:117]
	v_mfma_f32_16x16x32_bf16 v[106:109], v[174:177], v[182:185], v[106:109]
	v_mfma_f32_16x16x32_bf16 v[98:101], v[166:169], v[190:193], v[98:101]
	v_mfma_f32_16x16x32_bf16 v[90:93], v[174:177], v[190:193], v[90:93]
	v_mfma_f32_16x16x32_bf16 v[82:85], v[166:169], v[206:209], v[82:85]
	v_mfma_f32_16x16x32_bf16 v[74:77], v[174:177], v[206:209], v[74:77]
	v_mfma_f32_16x16x32_bf16 v[70:73], v[166:169], v[224:227], v[70:73]
	v_mfma_f32_16x16x32_bf16 v[66:69], v[174:177], v[224:227], v[66:69]
	s_setprio 0
	s_barrier
	s_add_i32 s42, s45, s54
	v_lshl_add_u64 v[140:141], v[140:141], 0, s[84:85]
	s_mov_b32 m0, s42
	ds_read_b128 v[178:181], v145 offset:49152
	ds_read_b128 v[182:185], v145 offset:50176
	ds_read_b128 v[186:189], v145 offset:51200
	ds_read_b128 v[190:193], v145 offset:52224
	ds_read_b128 v[202:205], v145 offset:53248
	ds_read_b128 v[206:209], v145 offset:54272
	ds_read_b128 v[220:223], v145 offset:55296
	ds_read_b128 v[224:227], v145 offset:56320
	global_load_lds_dwordx4 v[140:141], off
	v_lshl_add_u64 v[140:141], v[194:195], 0, s[84:85]
	s_add_i32 m0, s42, 0x2000
	s_add_i32 s42, s73, s54
	global_load_lds_dwordx4 v[140:141], off
	v_lshl_add_u64 v[140:141], v[198:199], 0, s[84:85]
	s_mov_b32 m0, s42
	s_nop 0
	global_load_lds_dwordx4 v[140:141], off
	v_lshl_add_u64 v[140:141], v[200:201], 0, s[84:85]
	s_add_i32 m0, s42, 0x2000
	s_nop 0
	global_load_lds_dwordx4 v[140:141], off
	v_lshl_add_u64 v[140:141], v[210:211], 0, s[84:85]
	s_mov_b32 m0, s64
	s_nop 0
	global_load_lds_dwordx4 v[140:141], off
	v_lshl_add_u64 v[140:141], v[212:213], 0, s[84:85]
	s_mov_b32 m0, s65
	s_nop 0
	global_load_lds_dwordx4 v[140:141], off
	s_waitcnt vmcnt(8)
	s_waitcnt lgkmcnt(0)
	s_barrier
	s_setprio 1
	s_waitcnt lgkmcnt(0)
	v_mfma_f32_16x16x32_bf16 v[62:65], v[146:149], v[178:181], v[62:65]
	v_mfma_f32_16x16x32_bf16 v[58:61], v[154:157], v[178:181], v[58:61]
	v_mfma_f32_16x16x32_bf16 v[54:57], v[146:149], v[186:189], v[54:57]
	v_mfma_f32_16x16x32_bf16 v[46:49], v[154:157], v[186:189], v[46:49]
	v_mfma_f32_16x16x32_bf16 v[38:41], v[146:149], v[202:205], v[38:41]
	v_mfma_f32_16x16x32_bf16 v[30:33], v[154:157], v[202:205], v[30:33]
	v_mfma_f32_16x16x32_bf16 v[22:25], v[146:149], v[220:223], v[22:25]
	v_mfma_f32_16x16x32_bf16 v[14:17], v[154:157], v[220:223], v[14:17]
	v_mfma_f32_16x16x32_bf16 v[62:65], v[150:153], v[182:185], v[62:65]
	v_mfma_f32_16x16x32_bf16 v[58:61], v[158:161], v[182:185], v[58:61]
	v_mfma_f32_16x16x32_bf16 v[54:57], v[150:153], v[190:193], v[54:57]
	v_mfma_f32_16x16x32_bf16 v[46:49], v[158:161], v[190:193], v[46:49]
	v_mfma_f32_16x16x32_bf16 v[38:41], v[150:153], v[206:209], v[38:41]
	v_mfma_f32_16x16x32_bf16 v[30:33], v[158:161], v[206:209], v[30:33]
	v_mfma_f32_16x16x32_bf16 v[22:25], v[150:153], v[224:227], v[22:25]
	v_mfma_f32_16x16x32_bf16 v[14:17], v[158:161], v[224:227], v[14:17]
	s_setprio 0
	s_setprio 1
	v_mfma_f32_16x16x32_bf16 v[50:53], v[162:165], v[178:181], v[50:53]
	v_mfma_f32_16x16x32_bf16 v[42:45], v[170:173], v[178:181], v[42:45]
	v_mfma_f32_16x16x32_bf16 v[34:37], v[162:165], v[186:189], v[34:37]
	v_mfma_f32_16x16x32_bf16 v[26:29], v[170:173], v[186:189], v[26:29]
	v_mfma_f32_16x16x32_bf16 v[18:21], v[162:165], v[202:205], v[18:21]
	v_mfma_f32_16x16x32_bf16 v[10:13], v[170:173], v[202:205], v[10:13]
	v_mfma_f32_16x16x32_bf16 v[6:9], v[162:165], v[220:223], v[6:9]
	v_mfma_f32_16x16x32_bf16 v[2:5], v[170:173], v[220:223], v[2:5]
	v_mfma_f32_16x16x32_bf16 v[50:53], v[166:169], v[182:185], v[50:53]
	v_mfma_f32_16x16x32_bf16 v[42:45], v[174:177], v[182:185], v[42:45]
	v_mfma_f32_16x16x32_bf16 v[34:37], v[166:169], v[190:193], v[34:37]
	v_mfma_f32_16x16x32_bf16 v[26:29], v[174:177], v[190:193], v[26:29]
	v_mfma_f32_16x16x32_bf16 v[18:21], v[166:169], v[206:209], v[18:21]
	v_mfma_f32_16x16x32_bf16 v[10:13], v[174:177], v[206:209], v[10:13]
	v_mfma_f32_16x16x32_bf16 v[6:9], v[166:169], v[224:227], v[6:9]
	v_mfma_f32_16x16x32_bf16 v[2:5], v[174:177], v[224:227], v[2:5]
	s_setprio 0
	s_barrier
	s_add_u32 vcc_lo, vcc_lo, 0x100
	s_addc_u32 vcc_hi, vcc_hi, 0
	s_add_u32 s82, s82, 0x100
	s_addc_u32 s83, s83, 0
	s_cmp_ge_u32 s72, s66
	s_mov_b32 s42, s72
	s_cbranch_scc1 .Lpeel_exit_bf

.Lpeel_exit_bf:
	s_and_b64 vcc, exec, s[86:87]
	s_cbranch_vccz .LBB0_311
	s_barrier

.LBB0_351:
	s_add_u32 s8, s76, 0x80
	s_addc_u32 s9, s77, 0
	s_add_u32 s59, s36, 0x100
	s_addc_u32 s60, s37, 0
	s_mov_b32 s36, 0
	s_add_i32 s61, s36, 2
	s_add_u32 s45, s8, 0x80
	s_addc_u32 s37, s9, 0
	s_add_i32 s64, 0, 0x10000
	s_cmp_eq_u32 s48, s36
	s_cselect_b32 s37, s39, s37
	s_cselect_b32 s36, s38, s45
	s_cselect_b32 s63, s41, s60
	s_cselect_b32 s62, s40, s59
	s_add_i32 s45, 0, 0x14000
	v_add_u32_e32 v158, s64, v148
	v_add_u32_e32 v174, s45, v148
	ds_read_b128 v[144:147], v158
	ds_read_b128 v[150:153], v158 offset:1024
	ds_read_b128 v[154:157], v158 offset:2048
	ds_read_b128 v[158:161], v158 offset:3072
	ds_read_b128 v[162:165], v174
	ds_read_b128 v[166:169], v174 offset:1024
	ds_read_b128 v[170:173], v174 offset:2048
	ds_read_b128 v[174:177], v174 offset:3072
	v_lshl_add_u64 v[194:195], s[8:9], 0, v[140:141]
	s_add_i32 m0, s82, 0xc000
	ds_read_b128 v[178:181], v149
	ds_read_b128 v[182:185], v149 offset:1024
	ds_read_b128 v[186:189], v149 offset:2048
	ds_read_b128 v[190:193], v149 offset:3072
	ds_read_b128 v[202:205], v149 offset:4096
	ds_read_b128 v[206:209], v149 offset:5120
	ds_read_b128 v[220:223], v149 offset:6144
	ds_read_b128 v[224:227], v149 offset:7168
	global_load_lds_dwordx4 v[194:195], off
	v_lshl_add_u64 v[194:195], s[8:9], 0, v[142:143]
	s_add_i32 m0, s82, 0xe000
	s_nop 0
	global_load_lds_dwordx4 v[194:195], off
	s_waitcnt vmcnt(8)
	s_waitcnt lgkmcnt(0)
	s_barrier
	s_setprio 1
	s_waitcnt lgkmcnt(0)
	v_mfma_f32_16x16x32_bf16 v[126:129], v[144:147], v[178:181], 0
	v_mfma_f32_16x16x32_bf16 v[122:125], v[154:157], v[178:181], 0
	v_mfma_f32_16x16x32_bf16 v[110:113], v[144:147], v[186:189], 0
	v_mfma_f32_16x16x32_bf16 v[106:109], v[154:157], v[186:189], 0
	v_mfma_f32_16x16x32_bf16 v[94:97], v[144:147], v[202:205], 0
	v_mfma_f32_16x16x32_bf16 v[90:93], v[154:157], v[202:205], 0
	v_mfma_f32_16x16x32_bf16 v[78:81], v[144:147], v[220:223], 0
	v_mfma_f32_16x16x32_bf16 v[74:77], v[154:157], v[220:223], 0
	v_mfma_f32_16x16x32_bf16 v[126:129], v[150:153], v[182:185], v[126:129]
	v_mfma_f32_16x16x32_bf16 v[122:125], v[158:161], v[182:185], v[122:125]
	v_mfma_f32_16x16x32_bf16 v[110:113], v[150:153], v[190:193], v[110:113]
	v_mfma_f32_16x16x32_bf16 v[106:109], v[158:161], v[190:193], v[106:109]
	v_mfma_f32_16x16x32_bf16 v[94:97], v[150:153], v[206:209], v[94:97]
	v_mfma_f32_16x16x32_bf16 v[90:93], v[158:161], v[206:209], v[90:93]
	v_mfma_f32_16x16x32_bf16 v[78:81], v[150:153], v[224:227], v[78:81]
	v_mfma_f32_16x16x32_bf16 v[74:77], v[158:161], v[224:227], v[74:77]
	s_setprio 0
	s_setprio 1
	v_mfma_f32_16x16x32_bf16 v[118:121], v[162:165], v[178:181], 0
	v_mfma_f32_16x16x32_bf16 v[114:117], v[170:173], v[178:181], 0
	v_mfma_f32_16x16x32_bf16 v[102:105], v[162:165], v[186:189], 0
	v_mfma_f32_16x16x32_bf16 v[98:101], v[170:173], v[186:189], 0
	v_mfma_f32_16x16x32_bf16 v[86:89], v[162:165], v[202:205], 0
	v_mfma_f32_16x16x32_bf16 v[82:85], v[170:173], v[202:205], 0
	v_mfma_f32_16x16x32_bf16 v[70:73], v[162:165], v[220:223], 0
	v_mfma_f32_16x16x32_bf16 v[66:69], v[170:173], v[220:223], 0
	v_mfma_f32_16x16x32_bf16 v[118:121], v[166:169], v[182:185], v[118:121]
	v_mfma_f32_16x16x32_bf16 v[114:117], v[174:177], v[182:185], v[114:117]
	v_mfma_f32_16x16x32_bf16 v[102:105], v[166:169], v[190:193], v[102:105]
	v_mfma_f32_16x16x32_bf16 v[98:101], v[174:177], v[190:193], v[98:101]
	v_mfma_f32_16x16x32_bf16 v[86:89], v[166:169], v[206:209], v[86:89]
	v_mfma_f32_16x16x32_bf16 v[82:85], v[174:177], v[206:209], v[82:85]
	v_mfma_f32_16x16x32_bf16 v[70:73], v[166:169], v[224:227], v[70:73]
	v_mfma_f32_16x16x32_bf16 v[66:69], v[174:177], v[224:227], v[66:69]
	s_setprio 0
	s_barrier
	s_add_i32 s64, s64, s79
	v_lshl_add_u64 v[194:195], s[62:63], 0, v[132:133]
	s_mov_b32 m0, s64
	ds_read_b128 v[178:181], v149 offset:16384
	ds_read_b128 v[182:185], v149 offset:17408
	ds_read_b128 v[186:189], v149 offset:18432
	ds_read_b128 v[190:193], v149 offset:19456
	ds_read_b128 v[202:205], v149 offset:20480
	ds_read_b128 v[206:209], v149 offset:21504
	ds_read_b128 v[220:223], v149 offset:22528
	ds_read_b128 v[224:227], v149 offset:23552
	global_load_lds_dwordx4 v[194:195], off
	s_add_i32 m0, s64, 0x2000
	v_lshl_add_u64 v[198:199], s[62:63], 0, v[136:137]
	s_add_u32 s62, s62, s80
	s_addc_u32 s63, s63, 0
	s_add_i32 s45, s45, s79
	global_load_lds_dwordx4 v[198:199], off
	v_lshl_add_u64 v[200:201], s[62:63], 0, v[132:133]
	s_mov_b32 m0, s45
	v_lshl_add_u64 v[210:211], s[62:63], 0, v[136:137]
	global_load_lds_dwordx4 v[200:201], off
	s_add_i32 m0, s45, 0x2000
	v_lshl_add_u64 v[212:213], s[36:37], 0, v[130:131]
	global_load_lds_dwordx4 v[210:211], off
	s_mov_b32 m0, s82
	v_lshl_add_u64 v[214:215], s[36:37], 0, v[134:135]
	global_load_lds_dwordx4 v[212:213], off
	s_mov_b32 m0, s83
	s_nop 0
	global_load_lds_dwordx4 v[214:215], off
	s_waitcnt vmcnt(8)
	s_waitcnt lgkmcnt(0)
	s_barrier
	s_setprio 1
	s_waitcnt lgkmcnt(0)
	v_mfma_f32_16x16x32_bf16 v[62:65], v[144:147], v[178:181], 0
	v_mfma_f32_16x16x32_bf16 v[58:61], v[154:157], v[178:181], 0
	v_mfma_f32_16x16x32_bf16 v[46:49], v[144:147], v[186:189], 0
	v_mfma_f32_16x16x32_bf16 v[42:45], v[154:157], v[186:189], 0
	v_mfma_f32_16x16x32_bf16 v[30:33], v[144:147], v[202:205], 0
	v_mfma_f32_16x16x32_bf16 v[26:29], v[154:157], v[202:205], 0
	v_mfma_f32_16x16x32_bf16 v[14:17], v[144:147], v[220:223], 0
	v_mfma_f32_16x16x32_bf16 v[10:13], v[154:157], v[220:223], 0
	v_mfma_f32_16x16x32_bf16 v[62:65], v[150:153], v[182:185], v[62:65]
	v_mfma_f32_16x16x32_bf16 v[58:61], v[158:161], v[182:185], v[58:61]
	v_mfma_f32_16x16x32_bf16 v[46:49], v[150:153], v[190:193], v[46:49]
	v_mfma_f32_16x16x32_bf16 v[42:45], v[158:161], v[190:193], v[42:45]
	v_mfma_f32_16x16x32_bf16 v[30:33], v[150:153], v[206:209], v[30:33]
	v_mfma_f32_16x16x32_bf16 v[26:29], v[158:161], v[206:209], v[26:29]
	v_mfma_f32_16x16x32_bf16 v[14:17], v[150:153], v[224:227], v[14:17]
	v_mfma_f32_16x16x32_bf16 v[10:13], v[158:161], v[224:227], v[10:13]
	s_setprio 0
	s_setprio 1
	v_mfma_f32_16x16x32_bf16 v[54:57], v[162:165], v[178:181], 0
	v_mfma_f32_16x16x32_bf16 v[50:53], v[170:173], v[178:181], 0
	v_mfma_f32_16x16x32_bf16 v[38:41], v[162:165], v[186:189], 0
	v_mfma_f32_16x16x32_bf16 v[34:37], v[170:173], v[186:189], 0
	v_mfma_f32_16x16x32_bf16 v[22:25], v[162:165], v[202:205], 0
	v_mfma_f32_16x16x32_bf16 v[18:21], v[170:173], v[202:205], 0
	v_mfma_f32_16x16x32_bf16 v[6:9], v[162:165], v[220:223], 0
	v_mfma_f32_16x16x32_bf16 v[2:5], v[170:173], v[220:223], 0
	v_mfma_f32_16x16x32_bf16 v[54:57], v[166:169], v[182:185], v[54:57]
	v_mfma_f32_16x16x32_bf16 v[50:53], v[174:177], v[182:185], v[50:53]
	v_mfma_f32_16x16x32_bf16 v[38:41], v[166:169], v[190:193], v[38:41]
	v_mfma_f32_16x16x32_bf16 v[34:37], v[174:177], v[190:193], v[34:37]
	v_mfma_f32_16x16x32_bf16 v[22:25], v[166:169], v[206:209], v[22:25]
	v_mfma_f32_16x16x32_bf16 v[18:21], v[174:177], v[206:209], v[18:21]
	v_mfma_f32_16x16x32_bf16 v[6:9], v[166:169], v[224:227], v[6:9]
	v_mfma_f32_16x16x32_bf16 v[2:5], v[174:177], v[224:227], v[2:5]
	s_setprio 0
	s_barrier
	s_add_i32 s45, 0, 0x18000
	s_add_i32 s62, 0, 0x1c000
	v_add_u32_e32 v158, s45, v148
	v_add_u32_e32 v174, s62, v148
	ds_read_b128 v[144:147], v158
	ds_read_b128 v[150:153], v158 offset:1024
	ds_read_b128 v[154:157], v158 offset:2048
	ds_read_b128 v[158:161], v158 offset:3072
	ds_read_b128 v[162:165], v174
	ds_read_b128 v[166:169], v174 offset:1024
	ds_read_b128 v[170:173], v174 offset:2048
	ds_read_b128 v[174:177], v174 offset:3072
	s_add_u32 s36, s36, s80
	s_addc_u32 s37, s37, 0
	s_mov_b32 m0, s86
	v_lshl_add_u64 v[216:217], s[36:37], 0, v[130:131]
	ds_read_b128 v[178:181], v149 offset:32768
	ds_read_b128 v[182:185], v149 offset:33792
	ds_read_b128 v[186:189], v149 offset:34816
	ds_read_b128 v[190:193], v149 offset:35840
	ds_read_b128 v[202:205], v149 offset:36864
	ds_read_b128 v[206:209], v149 offset:37888
	ds_read_b128 v[220:223], v149 offset:38912
	ds_read_b128 v[224:227], v149 offset:39936
	global_load_lds_dwordx4 v[216:217], off
	v_lshl_add_u64 v[216:217], s[36:37], 0, v[134:135]
	s_mov_b32 m0, s87
	s_nop 0
	global_load_lds_dwordx4 v[216:217], off
	s_waitcnt vmcnt(8)
	s_waitcnt lgkmcnt(0)
	s_barrier
	s_setprio 1
	s_waitcnt lgkmcnt(0)
	v_mfma_f32_16x16x32_bf16 v[126:129], v[144:147], v[178:181], v[126:129]
	v_mfma_f32_16x16x32_bf16 v[122:125], v[154:157], v[178:181], v[122:125]
	v_mfma_f32_16x16x32_bf16 v[110:113], v[144:147], v[186:189], v[110:113]
	v_mfma_f32_16x16x32_bf16 v[106:109], v[154:157], v[186:189], v[106:109]
	v_mfma_f32_16x16x32_bf16 v[94:97], v[144:147], v[202:205], v[94:97]
	v_mfma_f32_16x16x32_bf16 v[90:93], v[154:157], v[202:205], v[90:93]
	v_mfma_f32_16x16x32_bf16 v[78:81], v[144:147], v[220:223], v[78:81]
	v_mfma_f32_16x16x32_bf16 v[74:77], v[154:157], v[220:223], v[74:77]
	v_mfma_f32_16x16x32_bf16 v[126:129], v[150:153], v[182:185], v[126:129]
	v_mfma_f32_16x16x32_bf16 v[122:125], v[158:161], v[182:185], v[122:125]
	v_mfma_f32_16x16x32_bf16 v[110:113], v[150:153], v[190:193], v[110:113]
	v_mfma_f32_16x16x32_bf16 v[106:109], v[158:161], v[190:193], v[106:109]
	v_mfma_f32_16x16x32_bf16 v[94:97], v[150:153], v[206:209], v[94:97]
	v_mfma_f32_16x16x32_bf16 v[90:93], v[158:161], v[206:209], v[90:93]
	v_mfma_f32_16x16x32_bf16 v[78:81], v[150:153], v[224:227], v[78:81]
	v_mfma_f32_16x16x32_bf16 v[74:77], v[158:161], v[224:227], v[74:77]
	s_setprio 0
	s_setprio 1
	v_mfma_f32_16x16x32_bf16 v[118:121], v[162:165], v[178:181], v[118:121]
	v_mfma_f32_16x16x32_bf16 v[114:117], v[170:173], v[178:181], v[114:117]
	v_mfma_f32_16x16x32_bf16 v[102:105], v[162:165], v[186:189], v[102:105]
	v_mfma_f32_16x16x32_bf16 v[98:101], v[170:173], v[186:189], v[98:101]
	v_mfma_f32_16x16x32_bf16 v[86:89], v[162:165], v[202:205], v[86:89]
	v_mfma_f32_16x16x32_bf16 v[82:85], v[170:173], v[202:205], v[82:85]
	v_mfma_f32_16x16x32_bf16 v[70:73], v[162:165], v[220:223], v[70:73]
	v_mfma_f32_16x16x32_bf16 v[66:69], v[170:173], v[220:223], v[66:69]
	v_mfma_f32_16x16x32_bf16 v[118:121], v[166:169], v[182:185], v[118:121]
	v_mfma_f32_16x16x32_bf16 v[114:117], v[174:177], v[182:185], v[114:117]
	v_mfma_f32_16x16x32_bf16 v[102:105], v[166:169], v[190:193], v[102:105]
	v_mfma_f32_16x16x32_bf16 v[98:101], v[174:177], v[190:193], v[98:101]
	v_mfma_f32_16x16x32_bf16 v[86:89], v[166:169], v[206:209], v[86:89]
	v_mfma_f32_16x16x32_bf16 v[82:85], v[174:177], v[206:209], v[82:85]
	v_mfma_f32_16x16x32_bf16 v[70:73], v[166:169], v[224:227], v[70:73]
	v_mfma_f32_16x16x32_bf16 v[66:69], v[174:177], v[224:227], v[66:69]
	s_setprio 0
	s_barrier
	s_add_i32 s36, s45, s79
	v_lshl_add_u64 v[194:195], v[194:195], 0, s[84:85]
	s_mov_b32 m0, s36
	ds_read_b128 v[178:181], v149 offset:49152
	ds_read_b128 v[182:185], v149 offset:50176
	ds_read_b128 v[186:189], v149 offset:51200
	ds_read_b128 v[190:193], v149 offset:52224
	ds_read_b128 v[202:205], v149 offset:53248
	ds_read_b128 v[206:209], v149 offset:54272
	ds_read_b128 v[220:223], v149 offset:55296
	ds_read_b128 v[224:227], v149 offset:56320
	global_load_lds_dwordx4 v[194:195], off
	v_lshl_add_u64 v[194:195], v[198:199], 0, s[84:85]
	s_add_i32 m0, s36, 0x2000
	s_add_i32 s36, s62, s79
	global_load_lds_dwordx4 v[194:195], off
	v_lshl_add_u64 v[194:195], v[200:201], 0, s[84:85]
	s_mov_b32 m0, s36
	s_nop 0
	global_load_lds_dwordx4 v[194:195], off
	v_lshl_add_u64 v[194:195], v[210:211], 0, s[84:85]
	s_add_i32 m0, s36, 0x2000
	s_nop 0
	global_load_lds_dwordx4 v[194:195], off
	v_lshl_add_u64 v[194:195], v[212:213], 0, s[84:85]
	s_mov_b32 m0, s46
	s_nop 0
	global_load_lds_dwordx4 v[194:195], off
	v_lshl_add_u64 v[194:195], v[214:215], 0, s[84:85]
	s_mov_b32 m0, s47
	s_nop 0
	global_load_lds_dwordx4 v[194:195], off
	s_waitcnt vmcnt(8)
	s_waitcnt lgkmcnt(0)
	s_barrier
	s_setprio 1
	s_waitcnt lgkmcnt(0)
	v_mfma_f32_16x16x32_bf16 v[62:65], v[144:147], v[178:181], v[62:65]
	v_mfma_f32_16x16x32_bf16 v[58:61], v[154:157], v[178:181], v[58:61]
	v_mfma_f32_16x16x32_bf16 v[46:49], v[144:147], v[186:189], v[46:49]
	v_mfma_f32_16x16x32_bf16 v[42:45], v[154:157], v[186:189], v[42:45]
	v_mfma_f32_16x16x32_bf16 v[30:33], v[144:147], v[202:205], v[30:33]
	v_mfma_f32_16x16x32_bf16 v[26:29], v[154:157], v[202:205], v[26:29]
	v_mfma_f32_16x16x32_bf16 v[14:17], v[144:147], v[220:223], v[14:17]
	v_mfma_f32_16x16x32_bf16 v[10:13], v[154:157], v[220:223], v[10:13]
	v_mfma_f32_16x16x32_bf16 v[62:65], v[150:153], v[182:185], v[62:65]
	v_mfma_f32_16x16x32_bf16 v[58:61], v[158:161], v[182:185], v[58:61]
	v_mfma_f32_16x16x32_bf16 v[46:49], v[150:153], v[190:193], v[46:49]
	v_mfma_f32_16x16x32_bf16 v[42:45], v[158:161], v[190:193], v[42:45]
	v_mfma_f32_16x16x32_bf16 v[30:33], v[150:153], v[206:209], v[30:33]
	v_mfma_f32_16x16x32_bf16 v[26:29], v[158:161], v[206:209], v[26:29]
	v_mfma_f32_16x16x32_bf16 v[14:17], v[150:153], v[224:227], v[14:17]
	v_mfma_f32_16x16x32_bf16 v[10:13], v[158:161], v[224:227], v[10:13]
	s_setprio 0
	s_setprio 1
	v_mfma_f32_16x16x32_bf16 v[54:57], v[162:165], v[178:181], v[54:57]
	v_mfma_f32_16x16x32_bf16 v[50:53], v[170:173], v[178:181], v[50:53]
	v_mfma_f32_16x16x32_bf16 v[38:41], v[162:165], v[186:189], v[38:41]
	v_mfma_f32_16x16x32_bf16 v[34:37], v[170:173], v[186:189], v[34:37]
	v_mfma_f32_16x16x32_bf16 v[22:25], v[162:165], v[202:205], v[22:25]
	v_mfma_f32_16x16x32_bf16 v[18:21], v[170:173], v[202:205], v[18:21]
	v_mfma_f32_16x16x32_bf16 v[6:9], v[162:165], v[220:223], v[6:9]
	v_mfma_f32_16x16x32_bf16 v[2:5], v[170:173], v[220:223], v[2:5]
	v_mfma_f32_16x16x32_bf16 v[54:57], v[166:169], v[182:185], v[54:57]
	v_mfma_f32_16x16x32_bf16 v[50:53], v[174:177], v[182:185], v[50:53]
	v_mfma_f32_16x16x32_bf16 v[38:41], v[166:169], v[190:193], v[38:41]
	v_mfma_f32_16x16x32_bf16 v[34:37], v[174:177], v[190:193], v[34:37]
	v_mfma_f32_16x16x32_bf16 v[22:25], v[166:169], v[206:209], v[22:25]
	v_mfma_f32_16x16x32_bf16 v[18:21], v[174:177], v[206:209], v[18:21]
	v_mfma_f32_16x16x32_bf16 v[6:9], v[166:169], v[224:227], v[6:9]
	v_mfma_f32_16x16x32_bf16 v[2:5], v[174:177], v[224:227], v[2:5]
	s_setprio 0
	s_barrier
	s_add_u32 s8, s8, 0x100
	s_addc_u32 s9, s9, 0
	s_add_u32 s59, s59, 0x100
	s_addc_u32 s60, s60, 0
	s_cmp_ge_u32 s61, s90
	s_mov_b32 s36, s61
	s_cbranch_scc1 .Lpeel_exit_vt

.Lpeel_exit_vt:
	s_and_b64 vcc, exec, s[4:5]
	s_cbranch_vccz .LBB0_355
	s_barrier

.LBB0_691:
	s_ashr_i32 s15, s14, 31
	s_lshl_b64 s[16:17], s[14:15], 19
	s_add_u32 s16, s82, s16
	s_addc_u32 s17, s83, s17
	s_and_b64 s[18:19], s[6:7], exec
	s_cselect_b32 s15, s17, s5
	s_cselect_b32 s46, s16, s4
	s_ashr_i32 s11, s10, 31
	s_lshl_b64 s[18:19], s[10:11], 19
	s_add_u32 s18, s34, s18
	s_addc_u32 s19, s35, s19
	s_and_b64 s[28:29], s[6:7], exec
	s_cselect_b32 s11, s19, s21
	s_cselect_b32 s47, s18, s20
	s_add_u32 s4, s4, 0x40080
	s_addc_u32 s5, s5, 0
	s_add_u32 s48, s20, 0x100
	s_addc_u32 s49, s21, 0
	s_mov_b32 s50, -2
	s_add_u32 s20, s4, 0xfffc0080
	s_addc_u32 s21, s5, -1
	s_add_i32 s51, 0, 0x10000
	s_cmp_eq_u32 s50, 12
	s_cselect_b32 s29, s15, s21
	s_cselect_b32 s28, s46, s20
	v_add_u32_e32 v140, s51, v143
	s_cselect_b32 s21, s11, s49
	s_cselect_b32 s20, s47, s48
	s_add_i32 s54, 0, 0x14000
	ds_read_b128 v[146:149], v140
	ds_read_b128 v[150:153], v140 offset:1024
	ds_read_b128 v[154:157], v140 offset:2048
	ds_read_b128 v[158:161], v140 offset:3072
	v_add_u32_e32 v140, s54, v143
	ds_read_b128 v[162:165], v140
	ds_read_b128 v[166:169], v140 offset:1024
	ds_read_b128 v[170:173], v140 offset:2048
	ds_read_b128 v[174:177], v140 offset:3072
	v_lshl_add_u64 v[140:141], s[4:5], 0, v[136:137]
	s_add_i32 m0, s38, 0xc000
	ds_read_b128 v[178:181], v145
	ds_read_b128 v[182:185], v145 offset:1024
	ds_read_b128 v[186:189], v145 offset:2048
	ds_read_b128 v[190:193], v145 offset:3072
	ds_read_b128 v[202:205], v145 offset:4096
	ds_read_b128 v[206:209], v145 offset:5120
	ds_read_b128 v[220:223], v145 offset:6144
	ds_read_b128 v[224:227], v145 offset:7168
	global_load_lds_dwordx4 v[140:141], off
	v_lshl_add_u64 v[140:141], s[4:5], 0, v[138:139]
	s_add_i32 m0, s38, 0xe000
	s_nop 0
	global_load_lds_dwordx4 v[140:141], off
	s_waitcnt vmcnt(8)
	s_waitcnt lgkmcnt(0)
	s_barrier
	s_setprio 1
	s_waitcnt lgkmcnt(0)
	v_mfma_f32_16x16x32_bf16 v[126:129], v[146:149], v[178:181], 0
	v_mfma_f32_16x16x32_bf16 v[118:121], v[154:157], v[178:181], 0
	v_mfma_f32_16x16x32_bf16 v[110:113], v[146:149], v[186:189], 0
	v_mfma_f32_16x16x32_bf16 v[102:105], v[154:157], v[186:189], 0
	v_mfma_f32_16x16x32_bf16 v[94:97], v[146:149], v[202:205], 0
	v_mfma_f32_16x16x32_bf16 v[86:89], v[154:157], v[202:205], 0
	v_mfma_f32_16x16x32_bf16 v[78:81], v[146:149], v[220:223], 0
	v_mfma_f32_16x16x32_bf16 v[70:73], v[154:157], v[220:223], 0
	v_mfma_f32_16x16x32_bf16 v[126:129], v[150:153], v[182:185], v[126:129]
	v_mfma_f32_16x16x32_bf16 v[118:121], v[158:161], v[182:185], v[118:121]
	v_mfma_f32_16x16x32_bf16 v[110:113], v[150:153], v[190:193], v[110:113]
	v_mfma_f32_16x16x32_bf16 v[102:105], v[158:161], v[190:193], v[102:105]
	v_mfma_f32_16x16x32_bf16 v[94:97], v[150:153], v[206:209], v[94:97]
	v_mfma_f32_16x16x32_bf16 v[86:89], v[158:161], v[206:209], v[86:89]
	v_mfma_f32_16x16x32_bf16 v[78:81], v[150:153], v[224:227], v[78:81]
	v_mfma_f32_16x16x32_bf16 v[70:73], v[158:161], v[224:227], v[70:73]
	s_setprio 0
	s_setprio 1
	v_mfma_f32_16x16x32_bf16 v[122:125], v[162:165], v[178:181], 0
	v_mfma_f32_16x16x32_bf16 v[114:117], v[170:173], v[178:181], 0
	v_mfma_f32_16x16x32_bf16 v[106:109], v[162:165], v[186:189], 0
	v_mfma_f32_16x16x32_bf16 v[98:101], v[170:173], v[186:189], 0
	v_mfma_f32_16x16x32_bf16 v[90:93], v[162:165], v[202:205], 0
	v_mfma_f32_16x16x32_bf16 v[82:85], v[170:173], v[202:205], 0
	v_mfma_f32_16x16x32_bf16 v[74:77], v[162:165], v[220:223], 0
	v_mfma_f32_16x16x32_bf16 v[66:69], v[170:173], v[220:223], 0
	v_mfma_f32_16x16x32_bf16 v[122:125], v[166:169], v[182:185], v[122:125]
	v_mfma_f32_16x16x32_bf16 v[114:117], v[174:177], v[182:185], v[114:117]
	v_mfma_f32_16x16x32_bf16 v[106:109], v[166:169], v[190:193], v[106:109]
	v_mfma_f32_16x16x32_bf16 v[98:101], v[174:177], v[190:193], v[98:101]
	v_mfma_f32_16x16x32_bf16 v[90:93], v[166:169], v[206:209], v[90:93]
	v_mfma_f32_16x16x32_bf16 v[82:85], v[174:177], v[206:209], v[82:85]
	v_mfma_f32_16x16x32_bf16 v[74:77], v[166:169], v[224:227], v[74:77]
	v_mfma_f32_16x16x32_bf16 v[66:69], v[174:177], v[224:227], v[66:69]
	s_setprio 0
	s_barrier
	s_add_i32 s51, s51, s36
	v_lshl_add_u64 v[140:141], s[20:21], 0, v[0:1]
	s_mov_b32 m0, s51
	ds_read_b128 v[178:181], v145 offset:16384
	ds_read_b128 v[182:185], v145 offset:17408
	ds_read_b128 v[186:189], v145 offset:18432
	ds_read_b128 v[190:193], v145 offset:19456
	ds_read_b128 v[202:205], v145 offset:20480
	ds_read_b128 v[206:209], v145 offset:21504
	ds_read_b128 v[220:223], v145 offset:22528
	ds_read_b128 v[224:227], v145 offset:23552
	global_load_lds_dwordx4 v[140:141], off
	s_add_i32 m0, s51, 0x2000
	s_add_u32 s52, s20, 0x40000
	v_lshl_add_u64 v[194:195], s[20:21], 0, v[130:131]
	s_addc_u32 s53, s21, 0
	s_add_i32 s51, s54, s36
	global_load_lds_dwordx4 v[194:195], off
	v_lshl_add_u64 v[198:199], s[52:53], 0, v[0:1]
	s_mov_b32 m0, s51
	v_lshl_add_u64 v[200:201], s[28:29], 0, v[132:133]
	global_load_lds_dwordx4 v[198:199], off
	v_lshl_add_u64 v[198:199], s[52:53], 0, v[130:131]
	s_add_i32 m0, s51, 0x2000
	s_nop 0
	global_load_lds_dwordx4 v[198:199], off
	v_lshl_add_u64 v[198:199], s[28:29], 0, v[134:135]
	s_mov_b32 m0, s38
	s_nop 0
	global_load_lds_dwordx4 v[198:199], off
	s_mov_b32 m0, s39
	s_nop 0
	global_load_lds_dwordx4 v[200:201], off
	s_waitcnt vmcnt(8)
	s_waitcnt lgkmcnt(0)
	s_barrier
	s_setprio 1
	s_waitcnt lgkmcnt(0)
	v_mfma_f32_16x16x32_bf16 v[62:65], v[146:149], v[178:181], 0
	v_mfma_f32_16x16x32_bf16 v[54:57], v[154:157], v[178:181], 0
	v_mfma_f32_16x16x32_bf16 v[46:49], v[146:149], v[186:189], 0
	v_mfma_f32_16x16x32_bf16 v[38:41], v[154:157], v[186:189], 0
	v_mfma_f32_16x16x32_bf16 v[30:33], v[146:149], v[202:205], 0
	v_mfma_f32_16x16x32_bf16 v[22:25], v[154:157], v[202:205], 0
	v_mfma_f32_16x16x32_bf16 v[14:17], v[146:149], v[220:223], 0
	v_mfma_f32_16x16x32_bf16 v[6:9], v[154:157], v[220:223], 0
	v_mfma_f32_16x16x32_bf16 v[62:65], v[150:153], v[182:185], v[62:65]
	v_mfma_f32_16x16x32_bf16 v[54:57], v[158:161], v[182:185], v[54:57]
	v_mfma_f32_16x16x32_bf16 v[46:49], v[150:153], v[190:193], v[46:49]
	v_mfma_f32_16x16x32_bf16 v[38:41], v[158:161], v[190:193], v[38:41]
	v_mfma_f32_16x16x32_bf16 v[30:33], v[150:153], v[206:209], v[30:33]
	v_mfma_f32_16x16x32_bf16 v[22:25], v[158:161], v[206:209], v[22:25]
	v_mfma_f32_16x16x32_bf16 v[14:17], v[150:153], v[224:227], v[14:17]
	v_mfma_f32_16x16x32_bf16 v[6:9], v[158:161], v[224:227], v[6:9]
	s_setprio 0
	s_setprio 1
	v_mfma_f32_16x16x32_bf16 v[58:61], v[162:165], v[178:181], 0
	v_mfma_f32_16x16x32_bf16 v[50:53], v[170:173], v[178:181], 0
	v_mfma_f32_16x16x32_bf16 v[42:45], v[162:165], v[186:189], 0
	v_mfma_f32_16x16x32_bf16 v[34:37], v[170:173], v[186:189], 0
	v_mfma_f32_16x16x32_bf16 v[26:29], v[162:165], v[202:205], 0
	v_mfma_f32_16x16x32_bf16 v[18:21], v[170:173], v[202:205], 0
	v_mfma_f32_16x16x32_bf16 v[10:13], v[162:165], v[220:223], 0
	v_mfma_f32_16x16x32_bf16 v[2:5], v[170:173], v[220:223], 0
	v_mfma_f32_16x16x32_bf16 v[58:61], v[166:169], v[182:185], v[58:61]
	v_mfma_f32_16x16x32_bf16 v[50:53], v[174:177], v[182:185], v[50:53]
	v_mfma_f32_16x16x32_bf16 v[42:45], v[166:169], v[190:193], v[42:45]
	v_mfma_f32_16x16x32_bf16 v[34:37], v[174:177], v[190:193], v[34:37]
	v_mfma_f32_16x16x32_bf16 v[26:29], v[166:169], v[206:209], v[26:29]
	v_mfma_f32_16x16x32_bf16 v[18:21], v[174:177], v[206:209], v[18:21]
	v_mfma_f32_16x16x32_bf16 v[10:13], v[166:169], v[224:227], v[10:13]
	v_mfma_f32_16x16x32_bf16 v[2:5], v[174:177], v[224:227], v[2:5]
	s_setprio 0
	s_barrier
	s_add_i32 s51, 0, 0x18000
	s_add_i32 s52, 0, 0x1c000
	v_add_u32_e32 v158, s51, v143
	v_add_u32_e32 v174, s52, v143
	ds_read_b128 v[146:149], v158
	ds_read_b128 v[150:153], v158 offset:1024
	ds_read_b128 v[154:157], v158 offset:2048
	ds_read_b128 v[158:161], v158 offset:3072
	ds_read_b128 v[162:165], v174
	ds_read_b128 v[166:169], v174 offset:1024
	ds_read_b128 v[170:173], v174 offset:2048
	ds_read_b128 v[174:177], v174 offset:3072
	s_add_u32 s28, s28, 0x40000
	s_addc_u32 s29, s29, 0
	s_mov_b32 m0, s40
	v_lshl_add_u64 v[210:211], s[28:29], 0, v[134:135]
	ds_read_b128 v[178:181], v145 offset:32768
	ds_read_b128 v[182:185], v145 offset:33792
	ds_read_b128 v[186:189], v145 offset:34816
	ds_read_b128 v[190:193], v145 offset:35840
	ds_read_b128 v[202:205], v145 offset:36864
	ds_read_b128 v[206:209], v145 offset:37888
	ds_read_b128 v[220:223], v145 offset:38912
	ds_read_b128 v[224:227], v145 offset:39936
	global_load_lds_dwordx4 v[210:211], off
	v_lshl_add_u64 v[210:211], s[28:29], 0, v[132:133]
	s_mov_b32 m0, s41
	s_nop 0
	global_load_lds_dwordx4 v[210:211], off
	s_waitcnt vmcnt(8)
	s_waitcnt lgkmcnt(0)
	s_barrier
	s_setprio 1
	s_waitcnt lgkmcnt(0)
	v_mfma_f32_16x16x32_bf16 v[126:129], v[146:149], v[178:181], v[126:129]
	v_mfma_f32_16x16x32_bf16 v[118:121], v[154:157], v[178:181], v[118:121]
	v_mfma_f32_16x16x32_bf16 v[110:113], v[146:149], v[186:189], v[110:113]
	v_mfma_f32_16x16x32_bf16 v[102:105], v[154:157], v[186:189], v[102:105]
	v_mfma_f32_16x16x32_bf16 v[94:97], v[146:149], v[202:205], v[94:97]
	v_mfma_f32_16x16x32_bf16 v[86:89], v[154:157], v[202:205], v[86:89]
	v_mfma_f32_16x16x32_bf16 v[78:81], v[146:149], v[220:223], v[78:81]
	v_mfma_f32_16x16x32_bf16 v[70:73], v[154:157], v[220:223], v[70:73]
	v_mfma_f32_16x16x32_bf16 v[126:129], v[150:153], v[182:185], v[126:129]
	v_mfma_f32_16x16x32_bf16 v[118:121], v[158:161], v[182:185], v[118:121]
	v_mfma_f32_16x16x32_bf16 v[110:113], v[150:153], v[190:193], v[110:113]
	v_mfma_f32_16x16x32_bf16 v[102:105], v[158:161], v[190:193], v[102:105]
	v_mfma_f32_16x16x32_bf16 v[94:97], v[150:153], v[206:209], v[94:97]
	v_mfma_f32_16x16x32_bf16 v[86:89], v[158:161], v[206:209], v[86:89]
	v_mfma_f32_16x16x32_bf16 v[78:81], v[150:153], v[224:227], v[78:81]
	v_mfma_f32_16x16x32_bf16 v[70:73], v[158:161], v[224:227], v[70:73]
	s_setprio 0
	s_setprio 1
	v_mfma_f32_16x16x32_bf16 v[122:125], v[162:165], v[178:181], v[122:125]
	v_mfma_f32_16x16x32_bf16 v[114:117], v[170:173], v[178:181], v[114:117]
	v_mfma_f32_16x16x32_bf16 v[106:109], v[162:165], v[186:189], v[106:109]
	v_mfma_f32_16x16x32_bf16 v[98:101], v[170:173], v[186:189], v[98:101]
	v_mfma_f32_16x16x32_bf16 v[90:93], v[162:165], v[202:205], v[90:93]
	v_mfma_f32_16x16x32_bf16 v[82:85], v[170:173], v[202:205], v[82:85]
	v_mfma_f32_16x16x32_bf16 v[74:77], v[162:165], v[220:223], v[74:77]
	v_mfma_f32_16x16x32_bf16 v[66:69], v[170:173], v[220:223], v[66:69]
	v_mfma_f32_16x16x32_bf16 v[122:125], v[166:169], v[182:185], v[122:125]
	v_mfma_f32_16x16x32_bf16 v[114:117], v[174:177], v[182:185], v[114:117]
	v_mfma_f32_16x16x32_bf16 v[106:109], v[166:169], v[190:193], v[106:109]
	v_mfma_f32_16x16x32_bf16 v[98:101], v[174:177], v[190:193], v[98:101]
	v_mfma_f32_16x16x32_bf16 v[90:93], v[166:169], v[206:209], v[90:93]
	v_mfma_f32_16x16x32_bf16 v[82:85], v[174:177], v[206:209], v[82:85]
	v_mfma_f32_16x16x32_bf16 v[74:77], v[166:169], v[224:227], v[74:77]
	v_mfma_f32_16x16x32_bf16 v[66:69], v[174:177], v[224:227], v[66:69]
	s_setprio 0
	s_barrier
	s_add_i32 s28, s51, s36
	v_lshl_add_u64 v[140:141], v[140:141], 0, s[84:85]
	s_mov_b32 m0, s28
	ds_read_b128 v[178:181], v145 offset:49152
	ds_read_b128 v[182:185], v145 offset:50176
	ds_read_b128 v[186:189], v145 offset:51200
	ds_read_b128 v[190:193], v145 offset:52224
	ds_read_b128 v[202:205], v145 offset:53248
	ds_read_b128 v[206:209], v145 offset:54272
	ds_read_b128 v[220:223], v145 offset:55296
	ds_read_b128 v[224:227], v145 offset:56320
	global_load_lds_dwordx4 v[140:141], off
	s_add_i32 m0, s28, 0x2000
	s_add_u32 s20, s20, 0x40080
	v_lshl_add_u64 v[140:141], v[194:195], 0, s[84:85]
	s_addc_u32 s21, s21, 0
	s_add_i32 s28, s52, s36
	global_load_lds_dwordx4 v[140:141], off
	v_lshl_add_u64 v[140:141], s[20:21], 0, v[0:1]
	s_mov_b32 m0, s28
	s_nop 0
	global_load_lds_dwordx4 v[140:141], off
	v_lshl_add_u64 v[140:141], s[20:21], 0, v[130:131]
	s_add_i32 m0, s28, 0x2000
	s_nop 0
	global_load_lds_dwordx4 v[140:141], off
	v_lshl_add_u64 v[140:141], v[198:199], 0, s[84:85]
	s_mov_b32 m0, s76
	s_nop 0
	global_load_lds_dwordx4 v[140:141], off
	v_lshl_add_u64 v[140:141], v[200:201], 0, s[84:85]
	s_mov_b32 m0, s77
	s_nop 0
	global_load_lds_dwordx4 v[140:141], off
	s_waitcnt vmcnt(8)
	s_waitcnt lgkmcnt(0)
	s_barrier
	s_setprio 1
	s_waitcnt lgkmcnt(0)
	v_mfma_f32_16x16x32_bf16 v[62:65], v[146:149], v[178:181], v[62:65]
	v_mfma_f32_16x16x32_bf16 v[54:57], v[154:157], v[178:181], v[54:57]
	v_mfma_f32_16x16x32_bf16 v[46:49], v[146:149], v[186:189], v[46:49]
	v_mfma_f32_16x16x32_bf16 v[38:41], v[154:157], v[186:189], v[38:41]
	v_mfma_f32_16x16x32_bf16 v[30:33], v[146:149], v[202:205], v[30:33]
	v_mfma_f32_16x16x32_bf16 v[22:25], v[154:157], v[202:205], v[22:25]
	v_mfma_f32_16x16x32_bf16 v[14:17], v[146:149], v[220:223], v[14:17]
	v_mfma_f32_16x16x32_bf16 v[6:9], v[154:157], v[220:223], v[6:9]
	v_mfma_f32_16x16x32_bf16 v[62:65], v[150:153], v[182:185], v[62:65]
	v_mfma_f32_16x16x32_bf16 v[54:57], v[158:161], v[182:185], v[54:57]
	v_mfma_f32_16x16x32_bf16 v[46:49], v[150:153], v[190:193], v[46:49]
	v_mfma_f32_16x16x32_bf16 v[38:41], v[158:161], v[190:193], v[38:41]
	v_mfma_f32_16x16x32_bf16 v[30:33], v[150:153], v[206:209], v[30:33]
	v_mfma_f32_16x16x32_bf16 v[22:25], v[158:161], v[206:209], v[22:25]
	v_mfma_f32_16x16x32_bf16 v[14:17], v[150:153], v[224:227], v[14:17]
	v_mfma_f32_16x16x32_bf16 v[6:9], v[158:161], v[224:227], v[6:9]
	s_setprio 0
	s_setprio 1
	v_mfma_f32_16x16x32_bf16 v[58:61], v[162:165], v[178:181], v[58:61]
	v_mfma_f32_16x16x32_bf16 v[50:53], v[170:173], v[178:181], v[50:53]
	v_mfma_f32_16x16x32_bf16 v[42:45], v[162:165], v[186:189], v[42:45]
	v_mfma_f32_16x16x32_bf16 v[34:37], v[170:173], v[186:189], v[34:37]
	v_mfma_f32_16x16x32_bf16 v[26:29], v[162:165], v[202:205], v[26:29]
	v_mfma_f32_16x16x32_bf16 v[18:21], v[170:173], v[202:205], v[18:21]
	v_mfma_f32_16x16x32_bf16 v[10:13], v[162:165], v[220:223], v[10:13]
	v_mfma_f32_16x16x32_bf16 v[2:5], v[170:173], v[220:223], v[2:5]
	v_mfma_f32_16x16x32_bf16 v[58:61], v[166:169], v[182:185], v[58:61]
	v_mfma_f32_16x16x32_bf16 v[50:53], v[174:177], v[182:185], v[50:53]
	v_mfma_f32_16x16x32_bf16 v[42:45], v[166:169], v[190:193], v[42:45]
	v_mfma_f32_16x16x32_bf16 v[34:37], v[174:177], v[190:193], v[34:37]
	v_mfma_f32_16x16x32_bf16 v[26:29], v[166:169], v[206:209], v[26:29]
	v_mfma_f32_16x16x32_bf16 v[18:21], v[174:177], v[206:209], v[18:21]
	v_mfma_f32_16x16x32_bf16 v[10:13], v[166:169], v[224:227], v[10:13]
	v_mfma_f32_16x16x32_bf16 v[2:5], v[174:177], v[224:227], v[2:5]
	s_setprio 0
	s_barrier
	s_add_i32 s50, s50, 2
	s_add_u32 s4, s4, 0x100
	s_addc_u32 s5, s5, 0
	s_add_u32 s48, s48, 0x100
	s_addc_u32 s49, s49, 0
	s_cmp_gt_u32 s50, 13
	s_cbranch_scc1 .Lpeel_exit_swi

.Lpeel_exit_swi:
	s_and_b64 vcc, exec, s[8:9]
	s_cbranch_vccz .LBB0_695
	s_barrier
